# ssd_b chain split into 12 segments; MLA -1e30 score init moved to skipped-block stubs
# baseline (speedup 1.0000x reference)
.LBB0_107:
	s_cmp_eq_u32 s6, 1
	s_mov_b64 s[0:1], -1
	s_cbranch_scc0 .LBB0_321
	v_readlane_b32 s0, v253, 48
	s_cmp_lt_i32 s0, 11
	s_movk_i32 s0, 0xc3c
	s_cselect_b32 s26, s0, 0x998
	s_add_i32 s4, s54, 1
	s_lshl_b32 s0, s4, 10
	s_mul_hi_i32 s9, s54, 0xb00000
	s_mul_i32 s8, s54, 0xb00000
	s_ashr_i32 s1, s0, 31
	s_ashr_i32 s55, s54, 31
	v_writelane_b32 v253, s8, 59
	v_writelane_b32 v255, s6, 7
	s_lshl_b32 s2, s4, 8
	s_mulk_i32 s4, 0x180
	v_writelane_b32 v253, s9, 60
	s_lshl_b64 s[8:9], s[54:55], 23
	s_lshl_b64 s[0:1], s[0:1], 2
	s_ashr_i32 s5, s4, 31
	v_writelane_b32 v255, s8, 11
	v_writelane_b32 v254, s0, 1
	s_ashr_i32 s3, s2, 31
	v_writelane_b32 v255, s9, 12
	v_writelane_b32 v254, s1, 2
	s_lshl_b64 s[0:1], s[4:5], 2
	v_writelane_b32 v255, s0, 13
	s_lshl_b32 s6, s54, 10
	s_ashr_i32 s7, s6, 31
	v_writelane_b32 v255, s1, 14
	s_lshl_b64 s[0:1], s[54:55], 20
	v_writelane_b32 v255, s0, 15
	v_mov_b32_e32 v1, v210
	s_nop 0
	v_writelane_b32 v255, s1, 16
	s_lshl_b64 s[0:1], s[2:3], 2
	v_writelane_b32 v255, s0, 17
	v_ashrrev_i32_e32 v224, 8, v1
	v_mul_i32_i24_e32 v225, 0x12400, v224
	v_writelane_b32 v255, s1, 18
	s_lshl_b64 s[0:1], s[6:7], 2
	v_writelane_b32 v255, s0, 9
	v_add_u32_e32 v226, 0xffffecd0, v224
	v_add_u32_e32 v227, 0xfffffb20, v224
	v_writelane_b32 v255, s1, 10
	v_writelane_b32 v255, s54, 3
	s_nop 1
	v_writelane_b32 v255, s55, 4
	v_writelane_b32 v255, s26, 5
	s_branch .LBB0_112

.LBB0_116:
	s_or_b64 exec, exec, s[0:1]
	s_waitcnt lgkmcnt(0)
	s_barrier
	ds_read_b32 v1, v247
	s_mov_b64 s[0:1], -1
	s_waitcnt lgkmcnt(0)
	v_cmp_le_i32_e32 vcc, s26, v1
	v_readfirstlane_b32 s80, v1
	s_cbranch_vccnz .LBB0_111
	s_cmp_gt_i32 s80, 0x5f
	s_cbranch_scc0 .LBB0_302
	s_cmpk_gt_u32 s80, 0x26f
	s_cbranch_scc0 .LBB0_236
	s_cmpk_gt_u32 s80, 0x477
	s_cbranch_scc0 .LBB0_227
	s_add_i32 s16, s80, 0xfffffb88
	s_cmpk_gt_u32 s16, 0x51f
	s_cbranch_scc0 .LBB0_180
	v_lshl_add_u32 v1, s80, 1, v226
	s_movk_i32 s0, 0x4bf
	v_cmp_lt_i32_e64 s[0:1], s0, v1
	s_and_saveexec_b64 s[2:3], s[0:1]
	s_xor_b64 s[2:3], exec, s[2:3]
	v_add_u32_e32 v1, 0xfffffb40, v1
	s_andn2_saveexec_b64 s[2:3], s[2:3]
	s_cbranch_execz .LBB0_149
	v_ashrrev_i32_e32 v2, 31, v1
	v_lshrrev_b32_e32 v2, 28, v2
	s_load_dwordx4 s[4:7], s[82:83], 0x10
	s_load_dwordx2 s[8:9], s[82:83], 0xe0
	v_add_u32_e32 v2, v1, v2
	v_mov_b32_e32 v9, v210
	v_ashrrev_i32_e32 v10, 4, v2
	v_lshlrev_b32_e32 v8, 6, v10
	v_and_b32_e32 v6, 63, v9
	v_or_b32_e32 v2, v6, v8
	s_movk_i32 s10, 0xfff
	v_cmp_lt_i32_e32 vcc, s10, v2
	s_mov_b64 s[10:11], -1
	s_and_saveexec_b64 s[12:13], vcc
	s_cbranch_execz .LBB0_130
	s_movk_i32 s10, 0x129f
	v_cmp_lt_u32_e32 vcc, s10, v2
	s_and_saveexec_b64 s[14:15], vcc
	s_xor_b64 s[14:15], exec, s[14:15]
	s_movk_i32 s10, 0x12b0
	v_add_u32_e32 v3, 0xfffffd60, v2
	v_cmp_gt_u32_e64 s[10:11], s10, v2
	s_nop 1
	v_cndmask_b32_e64 v2, v2, v3, s[10:11]
	s_andn2_saveexec_b64 s[14:15], s[14:15]
	v_add_u32_e32 v2, 16, v2
	s_or_b64 s[10:11], s[10:11], exec
	s_or_b64 exec, exec, s[14:15]
	s_orn2_b64 s[10:11], s[10:11], exec

.LBB0_236:
	s_andn2_b64 vcc, exec, s[0:1]
	s_cbranch_vccnz .LBB0_301
	s_sub_i32 s10, s80, 0x60
	v_mov_b32_e32 v13, v210
	s_lshr_b32 s0, s10, 3
	s_and_b32 s48, s0, 0x7e
	v_ashrrev_i32_e32 v1, 8, v13
	v_subrev_u32_e32 v2, s48, v1
	v_cmp_gt_i32_e64 s[0:1], 1, v2
	v_add_u32_e32 v199, 64, v2
	v_bfe_u32 v228, v13, 6, 2
	v_writelane_b32 v254, s0, 61
	v_and_b32_e32 v5, 31, v13
	v_cmp_lt_i32_e64 s[8:9], 0, v2
	v_writelane_b32 v254, s1, 62
	s_bfe_i32 s0, s80, 0x10003
	s_and_b32 s50, s0, 0x2080
	s_load_dwordx4 s[0:3], s[82:83], 0x138
	v_lshlrev_b32_e32 v27, 7, v199
	v_lshlrev_b32_e32 v2, 5, v228
	v_or3_b32 v198, v27, v2, v5
	v_or_b32_e32 v2, 0x2000, v5
	v_cndmask_b32_e64 v2, v198, v2, s[8:9]
	s_mov_b32 s51, 0
	v_ashrrev_i32_e32 v3, 31, v2
	s_waitcnt lgkmcnt(0)
	v_mov_b32_e32 v6, s0
	v_mov_b32_e32 v7, s1
	v_lshl_add_u64 v[2:3], s[50:51], 0, v[2:3]
	s_movk_i32 s4, 0x600
	s_and_b32 s11, s80, 7
	v_mad_u64_u32 v[6:7], s[0:1], v2, s4, v[6:7]
	v_readlane_b32 s12, v253, 7
	v_bfe_u32 v4, v13, 5, 1
	v_mad_i32_i24 v7, v3, s4, v7
	v_readlane_b32 s13, v253, 8
	s_mul_i32 s12, s11, 0xc0
	v_lshlrev_b32_e32 v196, 4, v4
	v_lshl_add_u64 v[2:3], v[6:7], 0, s[12:13]
	v_lshl_add_u64 v[2:3], v[2:3], 0, v[196:197]
	global_load_dwordx4 v[112:115], v[2:3], off
	global_load_dwordx4 v[116:119], v[2:3], off offset:32
	global_load_dwordx4 v[120:123], v[2:3], off offset:64
	global_load_dwordx4 v[124:127], v[2:3], off offset:96
	global_load_dwordx4 v[128:131], v[2:3], off offset:128
	global_load_dwordx4 v[132:135], v[2:3], off offset:160
	s_load_dwordx4 s[4:7], s[82:83], 0xb8
	v_ashrrev_i32_e32 v6, 3, v13
	v_ashrrev_i32_e32 v7, 31, v6
	v_lshl_add_u64 v[10:11], s[50:51], 0, v[6:7]
	v_lshlrev_b64 v[10:11], 10, v[10:11]
	v_lshlrev_b32_e32 v7, 3, v13
	v_ashrrev_i32_e32 v2, 2, v13
	s_waitcnt lgkmcnt(0)
	v_lshl_add_u64 v[10:11], s[4:5], 0, v[10:11]
	s_lshl_b32 s12, s11, 7
	v_and_b32_e32 v12, 56, v7
	s_lshl_b32 s0, s11, 6
	v_lshl_add_u64 v[10:11], v[10:11], 0, s[12:13]
	v_lshlrev_b32_e32 v14, 1, v12
	v_mov_b32_e32 v15, v197
	v_ashrrev_i32_e32 v3, 31, v2
	v_writelane_b32 v255, s0, 1
	v_lshl_add_u64 v[200:201], v[10:11], 0, v[14:15]
	v_lshl_add_u64 v[10:11], s[50:51], 0, v[2:3]
	s_lshl_b32 s0, s10, 6
	v_ashrrev_i32_e32 v29, 4, v13
	v_lshlrev_b64 v[10:11], 6, v[10:11]
	s_and_b32 s0, s0, 0x3c0
	v_mov_b32_e32 v8, s6
	v_mov_b32_e32 v9, s7
	v_lshl_add_u64 v[10:11], s[2:3], 0, v[10:11]
	v_and_b32_e32 v26, 24, v7
	v_add_u32_e32 v3, s0, v29
	s_movk_i32 s0, 0x4100
	s_movk_i32 s3, 0x68
	v_lshlrev_b32_e32 v14, 1, v26
	v_mad_i64_i32 v[8:9], s[0:1], v3, s0, v[8:9]
	v_lshlrev_b32_e32 v3, 4, v13
	v_mad_u64_u32 v[206:207], s[0:1], v6, s3, v[12:13]
	v_lshl_add_u64 v[202:203], v[10:11], 0, v[14:15]
	v_and_b32_e32 v10, 0xf0, v3
	v_mov_b32_e32 v11, v197
	s_mov_b32 s1, 0x10000
	v_lshl_add_u64 v[204:205], v[8:9], 0, v[10:11]
	v_add_co_u32_e32 v10, vcc, s1, v200
	v_and_b32_e32 v28, 0x70, v7
	global_load_dwordx4 v[6:9], v[200:201], off
	v_addc_co_u32_e32 v11, vcc, 0, v201, vcc
	v_lshlrev_b32_e32 v34, 2, v13
	global_load_dwordx4 v[10:13], v[10:11], off
	s_nop 0
	global_load_dwordx4 v[14:17], v[202:203], off
	global_load_dwordx4 v[18:21], v[204:205], off
	s_mov_b32 s2, 0x82000
	v_add_co_u32_e32 v30, vcc, s2, v204
	s_sub_i32 s0, 0x41, s48
	s_nop 0
	v_addc_co_u32_e32 v31, vcc, 0, v205, vcc
	global_load_dwordx4 v[22:25], v[30:31], off
	s_cmp_lg_u32 s48, 0
	s_cselect_b32 s78, s0, 64
	s_mov_b32 s0, 0x20000
	v_add_co_u32_e32 v32, vcc, s0, v200
	s_mov_b32 s0, 0x30000
	s_nop 0
	v_addc_co_u32_e32 v33, vcc, 0, v201, vcc
	global_load_dwordx4 v[136:139], v[32:33], off
	v_add_co_u32_e32 v32, vcc, s0, v200
	s_movk_i32 s0, 0x2000
	s_nop 0
	v_addc_co_u32_e32 v33, vcc, 0, v201, vcc
	global_load_dwordx4 v[140:143], v[32:33], off
	v_add_co_u32_e32 v32, vcc, s0, v202
	s_min_u32 s0, s78, 2
	s_nop 0
	v_addc_co_u32_e32 v33, vcc, 0, v203, vcc
	s_lshl_b32 s12, s0, 17
	global_load_dwordx4 v[148:151], v[32:33], off
	global_load_dwordx4 v[152:155], v[204:205], off offset:256
	global_load_dwordx4 v[160:163], v[30:31], off offset:256
	v_lshl_add_u64 v[30:31], v[200:201], 0, s[12:13]
	global_load_dwordx4 v[144:147], v[30:31], off
	v_add_co_u32_e32 v30, vcc, s1, v30
	s_lshl_b32 s12, s0, 13
	s_nop 0
	v_addc_co_u32_e32 v31, vcc, 0, v31, vcc
	global_load_dwordx4 v[156:159], v[30:31], off
	v_lshl_add_u64 v[30:31], v[202:203], 0, s[12:13]
	s_lshl_b32 s12, s0, 8
	s_mov_b32 s1, s13
	global_load_dwordx4 v[164:167], v[30:31], off
	v_writelane_b32 v253, s0, 7
	v_lshl_add_u64 v[30:31], v[204:205], 0, s[12:13]
	global_load_dwordx4 v[168:171], v[30:31], off
	v_writelane_b32 v253, s1, 8
	v_add_co_u32_e32 v30, vcc, s2, v30
	v_mad_u64_u32 v[208:209], s[0:1], v2, s3, v[26:27]
	s_nop 0
	v_addc_co_u32_e32 v31, vcc, 0, v31, vcc
	v_lshlrev_b32_e32 v3, 1, v206
	v_lshlrev_b32_e32 v2, 1, v208
	s_movk_i32 s0, 0x88
	global_load_dwordx4 v[172:175], v[30:31], off
	s_barrier
	s_waitcnt vmcnt(14)
	ds_write_b128 v3, v[6:9]
	s_waitcnt vmcnt(13)
	ds_write_b128 v3, v[10:13] offset:13312
	s_waitcnt vmcnt(12)
	ds_write_b128 v2, v[14:17] offset:128
	v_mad_u64_u32 v[2:3], s[0:1], v29, s0, v[28:29]
	v_and_or_b32 v209, v34, 4, v2
	v_lshlrev_b32_e32 v2, 1, v209
	v_add_u32_e32 v3, 0x6800, v2
	v_add_u32_e32 v2, 0x8800, v2
	v_lshlrev_b32_e32 v207, 2, v4
	s_waitcnt vmcnt(10)
	ds_write2_b64 v2, v[22:23], v[24:25] offset0:64 offset1:66
	v_or_b32_e32 v2, v27, v207
	v_cmp_gt_i32_e64 s[0:1], v2, v198
	ds_write2_b64 v3, v[18:19], v[20:21] offset1:2
	v_or_b32_e32 v3, 2, v2
	v_writelane_b32 v253, s0, 53
	v_mov_b32_e32 v30, v197
	v_mov_b32_e32 v31, v197
	v_writelane_b32 v253, s1, 54
	v_cmp_gt_i32_e64 s[0:1], v3, v198
	v_or_b32_e32 v3, 3, v2
	v_cmp_lt_i32_e64 s[12:13], v2, v198
	v_writelane_b32 v253, s0, 55
	v_mov_b32_e32 v16, v197
	v_mov_b32_e32 v17, v197
	v_writelane_b32 v253, s1, 56
	v_cmp_gt_i32_e64 s[0:1], v3, v198
	v_or_b32_e32 v3, 8, v2
	v_mov_b32_e32 v18, v197
	v_writelane_b32 v253, s0, 57
	v_mov_b32_e32 v19, v197
	v_mov_b32_e32 v20, v197
	v_writelane_b32 v253, s1, 58
	v_cmp_gt_i32_e64 s[0:1], v3, v198
	v_or_b32_e32 v3, 9, v2
	v_mov_b32_e32 v21, v197
	v_writelane_b32 v253, s0, 61
	v_mov_b32_e32 v22, v197
	v_mov_b32_e32 v23, v197
	v_writelane_b32 v253, s1, 62
	v_cmp_gt_i32_e64 s[0:1], v3, v198
	v_or_b32_e32 v3, 10, v2
	v_mov_b32_e32 v24, v197
	v_writelane_b32 v253, s0, 51
	v_mov_b32_e32 v25, v197
	v_mov_b32_e32 v26, v197
	v_writelane_b32 v253, s1, 52
	v_cmp_gt_i32_e64 s[0:1], v3, v198
	v_or_b32_e32 v3, 11, v2
	v_mov_b32_e32 v27, v197
	v_writelane_b32 v253, s0, 63
	v_mov_b32_e32 v28, v197
	v_mov_b32_e32 v29, v197
	v_writelane_b32 v254, s1, 0
	v_cmp_gt_i32_e64 s[0:1], v3, v198
	v_or_b32_e32 v3, 16, v2
	v_mov_b64_e32 v[46:47], v[30:31]
	v_writelane_b32 v254, s0, 35
	s_mov_b32 s81, 5
	v_mul_u32_u24_e32 v229, 0xd0, v5
	v_writelane_b32 v254, s1, 36
	v_cmp_gt_i32_e64 s[0:1], v3, v198
	v_or_b32_e32 v3, 17, v2
	v_mul_u32_u24_e32 v230, 0x110, v5
	v_writelane_b32 v254, s0, 39
	v_sub_u32_e32 v231, s48, v1
	v_mov_b32_e32 v238, 0xf149f2ca
	v_writelane_b32 v254, s1, 40
	v_cmp_gt_i32_e64 s[0:1], v3, v198
	v_or_b32_e32 v3, 18, v2
	v_mov_b32_e32 v232, 0
	v_writelane_b32 v254, s0, 43
	v_mov_b64_e32 v[44:45], v[28:29]
	v_mov_b64_e32 v[42:43], v[26:27]
	v_writelane_b32 v254, s1, 44
	v_cmp_gt_i32_e64 s[0:1], v3, v198
	v_or_b32_e32 v3, 19, v2
	v_mov_b64_e32 v[40:41], v[24:25]
	v_writelane_b32 v254, s0, 47
	v_mov_b64_e32 v[38:39], v[22:23]
	v_mov_b64_e32 v[36:37], v[20:21]
	v_writelane_b32 v254, s1, 48
	v_cmp_gt_i32_e64 s[0:1], v3, v198
	v_or_b32_e32 v3, 24, v2
	v_mov_b64_e32 v[34:35], v[18:19]
	v_writelane_b32 v254, s0, 51
	v_mov_b64_e32 v[32:33], v[16:17]
	s_waitcnt lgkmcnt(0)
	v_writelane_b32 v254, s1, 52
	v_cmp_gt_i32_e64 s[0:1], v3, v198
	v_or_b32_e32 v3, 25, v2
	s_barrier
; DI int crow(int reg, int hh) { return (reg & 3) + 8 * (reg >> 2) + 4 * hh; }
; DI void mla2_item(PP p, int item, unsigned char* lds) {
;     ...
;                 if (T == 0 || T == qblk) {
; #pragma unroll
;                     for (int kb = 0; kb < 4; ++kb)
; #pragma unroll
;                         for (int r = 0; r < 16; ++r) {
;                             const int k0 = key0 + kb * 32 + crow(r, hh);
;                             if (!((k0 <= qpos) && (k0 >= NPAD))) sc[kb][r] = -1e30f;
;                         }
	v_writelane_b32 v254, s0, 3
	s_nop 1
	v_writelane_b32 v254, s1, 4
	v_cmp_gt_i32_e64 s[0:1], v3, v198
	v_or_b32_e32 v3, 26, v2
	s_nop 0
	v_writelane_b32 v254, s0, 5
	s_nop 1
	v_writelane_b32 v254, s1, 6
	v_cmp_gt_i32_e64 s[0:1], v3, v198
	v_or_b32_e32 v3, 27, v2
	s_nop 0
	v_writelane_b32 v254, s0, 7
	s_nop 1
	v_writelane_b32 v254, s1, 8
	v_cmp_gt_i32_e64 s[0:1], v3, v198
	v_or_b32_e32 v3, 32, v2
	s_nop 0
	v_writelane_b32 v254, s0, 9
	s_nop 1
	v_writelane_b32 v254, s1, 10
	v_cmp_gt_i32_e64 s[0:1], v3, v198
	v_or_b32_e32 v3, 33, v2
	s_nop 0
	v_writelane_b32 v254, s0, 11
	s_nop 1
	v_writelane_b32 v254, s1, 12
	v_cmp_gt_i32_e64 s[0:1], v3, v198
	v_or_b32_e32 v3, 34, v2
	s_nop 0
	v_writelane_b32 v254, s0, 13
	s_nop 1
	v_writelane_b32 v254, s1, 14
	v_cmp_gt_i32_e64 s[0:1], v3, v198
	v_or_b32_e32 v3, 35, v2
	s_nop 0
	v_writelane_b32 v254, s0, 15
	s_nop 1
	v_writelane_b32 v254, s1, 16
	v_cmp_gt_i32_e64 s[0:1], v3, v198
	v_or_b32_e32 v3, 40, v2
	s_nop 0
	v_writelane_b32 v254, s0, 17
	s_nop 1
	v_writelane_b32 v254, s1, 18
	v_cmp_gt_i32_e64 s[0:1], v3, v198
	v_or_b32_e32 v3, 41, v2
	s_nop 0
	v_writelane_b32 v254, s0, 19
	s_nop 1
	v_writelane_b32 v254, s1, 20
	v_cmp_gt_i32_e64 s[0:1], v3, v198
	v_or_b32_e32 v3, 42, v2
	s_nop 0
	v_writelane_b32 v254, s0, 21
	s_nop 1
	v_writelane_b32 v254, s1, 22
	v_cmp_gt_i32_e64 s[0:1], v3, v198
	v_or_b32_e32 v3, 43, v2
	s_nop 0
	v_writelane_b32 v254, s0, 23
	s_nop 1
	v_writelane_b32 v254, s1, 24
	v_cmp_gt_i32_e64 s[0:1], v3, v198
	v_or_b32_e32 v3, 48, v2
	s_nop 0
	v_writelane_b32 v254, s0, 25
	s_nop 1
	v_writelane_b32 v254, s1, 26
	v_cmp_gt_i32_e64 s[0:1], v3, v198
	v_or_b32_e32 v3, 49, v2
	s_nop 0
	v_writelane_b32 v254, s0, 27
	s_nop 1
	v_writelane_b32 v254, s1, 28
	v_cmp_gt_i32_e64 s[0:1], v3, v198
	v_or_b32_e32 v3, 50, v2
	s_nop 0
	v_writelane_b32 v254, s0, 29
	s_nop 1
	v_writelane_b32 v254, s1, 30
	v_cmp_gt_i32_e64 s[0:1], v3, v198
	v_or_b32_e32 v3, 51, v2
	s_nop 0
	v_writelane_b32 v254, s0, 31
	s_nop 1
	v_writelane_b32 v254, s1, 32
	v_cmp_gt_i32_e64 s[0:1], v3, v198
	v_or_b32_e32 v3, 56, v2
	s_nop 0
	v_writelane_b32 v254, s0, 33
	s_nop 1
	v_writelane_b32 v254, s1, 34
	v_cmp_gt_i32_e64 s[0:1], v3, v198
	v_or_b32_e32 v3, 57, v2
	s_nop 0
	v_writelane_b32 v254, s0, 37
	s_nop 1
	v_writelane_b32 v254, s1, 38
	v_cmp_gt_i32_e64 s[0:1], v3, v198
	v_or_b32_e32 v3, 58, v2
	s_nop 0
	v_writelane_b32 v254, s0, 41
	s_nop 1
	v_writelane_b32 v254, s1, 42
	v_cmp_gt_i32_e64 s[0:1], v3, v198
	v_or_b32_e32 v3, 59, v2
	s_nop 0
	v_writelane_b32 v254, s0, 45
	s_nop 1
	v_writelane_b32 v254, s1, 46
	v_cmp_gt_i32_e64 s[0:1], v3, v198
	v_or_b32_e32 v3, 64, v2
	s_nop 0
	v_writelane_b32 v254, s0, 49
	s_nop 1
	v_writelane_b32 v254, s1, 50
	v_cmp_gt_i32_e64 s[0:1], v3, v198
	v_or_b32_e32 v3, 0x41, v2
	s_nop 0
	v_writelane_b32 v254, s0, 53
	s_nop 1
	v_writelane_b32 v254, s1, 54
	v_cmp_gt_i32_e64 s[0:1], v3, v198
	v_or_b32_e32 v3, 0x42, v2
	s_nop 0
	v_writelane_b32 v254, s0, 55
	s_nop 1
	v_writelane_b32 v254, s1, 56
	v_cmp_gt_i32_e64 s[0:1], v3, v198
	v_or_b32_e32 v3, 0x43, v2
	s_nop 0
	v_writelane_b32 v254, s0, 57
	s_nop 1
	v_writelane_b32 v254, s1, 58
	v_cmp_gt_i32_e64 s[0:1], v3, v198
	v_or_b32_e32 v3, 0x48, v2
	v_cmp_gt_i32_e64 s[84:85], v3, v198
	v_or_b32_e32 v3, 0x49, v2
	v_cmp_gt_i32_e64 s[86:87], v3, v198
	v_or_b32_e32 v3, 0x4a, v2
	v_cmp_gt_i32_e64 s[88:89], v3, v198
	v_or_b32_e32 v3, 0x4b, v2
	v_cmp_gt_i32_e64 s[90:91], v3, v198
	v_or_b32_e32 v3, 0x50, v2
	v_cmp_gt_i32_e64 s[92:93], v3, v198
	v_or_b32_e32 v3, 0x51, v2
	v_cmp_gt_i32_e64 s[94:95], v3, v198
	v_or_b32_e32 v3, 0x52, v2
	v_cmp_gt_i32_e64 s[96:97], v3, v198
	v_or_b32_e32 v3, 0x53, v2
	v_cmp_gt_i32_e64 s[4:5], v3, v198
	v_or_b32_e32 v3, 0x58, v2
	v_writelane_b32 v254, s0, 59
	v_cmp_gt_i32_e64 s[6:7], v3, v198
	v_or_b32_e32 v3, 0x59, v2
	v_writelane_b32 v254, s1, 60
	v_cmp_gt_i32_e64 s[0:1], v3, v198
	v_or_b32_e32 v3, 0x5a, v2
	v_cmp_gt_i32_e64 s[54:55], v3, v198
	v_or_b32_e32 v3, 0x5b, v2
	v_cmp_gt_i32_e64 s[10:11], v3, v198
	v_or_b32_e32 v3, 0x60, v2
	v_cmp_gt_i32_e64 s[14:15], v3, v198
	v_or_b32_e32 v3, 0x61, v2
	v_cmp_gt_i32_e64 s[16:17], v3, v198
	v_or_b32_e32 v3, 0x62, v2
	v_cmp_gt_i32_e64 s[18:19], v3, v198
	v_or_b32_e32 v3, 0x63, v2
	v_cmp_gt_i32_e64 s[68:69], v3, v198
	v_or_b32_e32 v3, 0x68, v2
	v_cmp_gt_i32_e64 s[74:75], v3, v198
	v_or_b32_e32 v3, 0x69, v2
	v_cmp_gt_i32_e64 s[76:77], v3, v198
	v_or_b32_e32 v3, 0x6a, v2
	v_cmp_gt_i32_e64 s[26:27], v3, v198
	v_or_b32_e32 v3, 0x6b, v2
	v_cmp_gt_i32_e64 s[28:29], v3, v198
	v_or_b32_e32 v3, 0x70, v2
	v_cmp_gt_i32_e64 s[30:31], v3, v198
	v_or_b32_e32 v3, 0x71, v2
	v_cmp_gt_i32_e64 s[34:35], v3, v198
	v_or_b32_e32 v3, 0x72, v2
	v_cmp_gt_i32_e64 s[36:37], v3, v198
	v_or_b32_e32 v3, 0x73, v2
	v_cmp_gt_i32_e64 s[38:39], v3, v198
	v_or_b32_e32 v3, 0x78, v2
	v_cmp_gt_i32_e64 s[40:41], v3, v198
	v_or_b32_e32 v3, 0x79, v2
	v_cmp_gt_i32_e64 s[42:43], v3, v198
	v_or_b32_e32 v3, 0x7a, v2
	v_or_b32_e32 v2, 0x7b, v2
	v_cmp_gt_i32_e64 s[44:45], v3, v198
	v_cmp_gt_i32_e64 s[46:47], v2, v198
	v_writelane_b32 v254, s50, 63
	s_mov_b32 s79, s51
	s_nop 0
	v_writelane_b32 v255, s51, 0
	s_branch .LBB0_241

; DI f32x16 mfma32(bf16x8 a, bf16x8 b, f32x16 c) { return __builtin_amdgcn_mfma_f32_32x32x16_bf16(a, b, c, 0, 0, 0); }
; DI f32x16 zero16() { f32x16 z; for (int i = 0; i < 16; ++i) z[i] = 0.f; return z; }
; DI void mla2_item(PP p, int item, unsigned char* lds) {
;     ...
;             { const int tn = (T + 3 < nt) ? T + 3 : nt - 1; M2_LOAD(u, tn); }
;             if (wvalid && T <= qblk) {
;                 const bf16_t* Kl = L0 + cur * M2STG;
;                 const bf16_t* Vl = Kl + M2K;
;                 const int key0 = T * 128;
;                 const int kbmax = (T < qblk) ? 3 : wi;
;                 f32x16 sc[4];
; #pragma unroll
;                 for (int kb = 0; kb < 4; ++kb) {
;                     if (kb <= kbmax) {
;                         sc[kb] = zero16();
; #pragma unroll
;                         for (int s6 = 0; s6 < 6; ++s6) sc[kb] = mfma32(ld16(Kl + (kb * 32 + l31) * KSTR + 16 * s6 + 8 * hh), qf[s6], sc[kb]);
;                     } else {
; #pragma unroll
;                         for (int r = 0; r < 16; ++r) sc[kb][r] = -1e30f;
;                     }
;                 }
.LBB0_241:
	v_readlane_b32 s2, v253, 7
	s_add_i32 s58, s81, -2
	v_readlane_b32 s3, v253, 8
	s_mov_b32 s49, s3
	s_min_i32 s48, s58, s78
	s_lshl_b64 s[2:3], s[48:49], 17
	v_lshl_add_u64 v[2:3], v[200:201], 0, s[2:3]
	s_mov_b32 s2, 0x10000
	v_add_co_u32_e32 v4, vcc, s2, v2
	s_lshl_b64 s[2:3], s[48:49], 13
	s_nop 0
	v_addc_co_u32_e32 v5, vcc, 0, v3, vcc
	global_load_dwordx4 v[176:179], v[2:3], off
	global_load_dwordx4 v[180:183], v[4:5], off
	v_lshl_add_u64 v[2:3], v[202:203], 0, s[2:3]
	s_mov_b32 s3, s49
	v_writelane_b32 v253, s2, 7
	global_load_dwordx4 v[184:187], v[2:3], off
	s_add_i32 s62, s81, -5
	v_writelane_b32 v253, s3, 8
	s_lshl_b64 s[2:3], s[48:49], 8
	v_lshl_add_u64 v[2:3], v[204:205], 0, s[2:3]
	v_add_co_u32_e32 v4, vcc, 0x82000, v2
	s_xor_b64 s[64:65], s[8:9], -1
	s_nop 0
	v_addc_co_u32_e32 v5, vcc, 0, v3, vcc
	global_load_dwordx4 v[192:195], v[2:3], off
	global_load_dwordx4 v[188:191], v[4:5], off
	v_cmp_le_i32_e32 vcc, s62, v199
	v_add_u32_e32 v233, s81, v231
	s_and_b32 s59, s62, 1
	s_and_b64 s[2:3], s[64:65], vcc
	s_and_saveexec_b64 s[66:67], s[2:3]
	s_cbranch_execz .LBB0_259
	s_mul_i32 s2, s59, 0xac00
	v_or_b32_e32 v234, s2, v196
	v_add_u32_e32 v235, v234, v229
	ds_read_b128 v[2:5], v235
	ds_read_b128 v[6:9], v235 offset:32
	v_cmp_ge_i32_e32 vcc, s62, v199
	s_waitcnt lgkmcnt(1)
	v_mfma_f32_32x32x16_bf16 v[80:95], v[2:5], v[112:115], 0
	v_cndmask_b32_e32 v1, 3, v228, vcc
	s_waitcnt lgkmcnt(0)
	v_mfma_f32_32x32x16_bf16 v[80:95], v[6:9], v[116:119], v[80:95]
	ds_read_b128 v[2:5], v235 offset:64
	ds_read_b128 v[6:9], v235 offset:96
	s_waitcnt lgkmcnt(1)
	v_mfma_f32_32x32x16_bf16 v[80:95], v[2:5], v[120:123], v[80:95]
	ds_read_b128 v[2:5], v235 offset:128
	v_cmp_ne_u32_e64 s[52:53], 0, v1
	s_waitcnt lgkmcnt(1)
	v_mfma_f32_32x32x16_bf16 v[80:95], v[6:9], v[124:127], v[80:95]
	ds_read_b128 v[6:9], v235 offset:160
	s_waitcnt lgkmcnt(1)
	v_mfma_f32_32x32x16_bf16 v[80:95], v[2:5], v[128:131], v[80:95]
	s_waitcnt lgkmcnt(0)
	v_mfma_f32_32x32x16_bf16 v[80:95], v[6:9], v[132:135], v[80:95]
	s_and_saveexec_b64 s[48:49], s[52:53]
	s_cbranch_execz .Lmla_init_0
	ds_read_b128 v[2:5], v235 offset:6656
	ds_read_b128 v[212:215], v235 offset:6688
	ds_read_b128 v[216:219], v235 offset:6720
	ds_read_b128 v[220:223], v235 offset:6752
	s_waitcnt lgkmcnt(3)
	v_mfma_f32_32x32x16_bf16 v[96:111], v[2:5], v[112:115], 0
	ds_read_b128 v[2:5], v235 offset:6784
	s_waitcnt lgkmcnt(3)
	v_mfma_f32_32x32x16_bf16 v[96:111], v[212:215], v[116:119], v[96:111]
	ds_read_b128 v[212:215], v235 offset:6816
	s_waitcnt lgkmcnt(3)
	v_mfma_f32_32x32x16_bf16 v[96:111], v[216:219], v[120:123], v[96:111]
	s_waitcnt lgkmcnt(2)
	v_mfma_f32_32x32x16_bf16 v[96:111], v[220:223], v[124:127], v[96:111]
	s_waitcnt lgkmcnt(1)
	v_mfma_f32_32x32x16_bf16 v[96:111], v[2:5], v[128:131], v[96:111]
	s_waitcnt lgkmcnt(0)
	v_mfma_f32_32x32x16_bf16 v[96:111], v[212:215], v[132:135], v[96:111]

; DI void mla2_item(PP p, int item, unsigned char* lds) {
;     ...
;                     } else {
; #pragma unroll
;                         for (int r = 0; r < 16; ++r) sc[kb][r] = -1e30f;
;                     }
.LBB0_246:
	s_or_b64 exec, exec, s[48:49]
	v_cmp_eq_u32_e64 s[48:49], 3, v1
	s_and_saveexec_b64 s[56:57], s[48:49]
	s_cbranch_execz .Lmla_init_2
	ds_read_b128 v[2:5], v235 offset:19968
	ds_read_b128 v[212:215], v235 offset:20000
	ds_read_b128 v[216:219], v235 offset:20032
	ds_read_b128 v[220:223], v235 offset:20064
	s_waitcnt lgkmcnt(3)
	v_mfma_f32_32x32x16_bf16 v[64:79], v[2:5], v[112:115], 0
	ds_read_b128 v[2:5], v235 offset:20096
	s_waitcnt lgkmcnt(3)
	v_mfma_f32_32x32x16_bf16 v[64:79], v[212:215], v[116:119], v[64:79]
	ds_read_b128 v[212:215], v235 offset:20128
	s_waitcnt lgkmcnt(3)
	v_mfma_f32_32x32x16_bf16 v[64:79], v[216:219], v[120:123], v[64:79]
	s_waitcnt lgkmcnt(2)
	v_mfma_f32_32x32x16_bf16 v[64:79], v[220:223], v[124:127], v[64:79]
	s_waitcnt lgkmcnt(1)
	v_mfma_f32_32x32x16_bf16 v[64:79], v[2:5], v[128:131], v[64:79]
	s_waitcnt lgkmcnt(0)
	v_mfma_f32_32x32x16_bf16 v[64:79], v[212:215], v[132:135], v[64:79]

; DI f32x16 mfma32(bf16x8 a, bf16x8 b, f32x16 c) { return __builtin_amdgcn_mfma_f32_32x32x16_bf16(a, b, c, 0, 0, 0); }
; DI f32x16 zero16() { f32x16 z; for (int i = 0; i < 16; ++i) z[i] = 0.f; return z; }
; DI void mla2_item(PP p, int item, unsigned char* lds) {
;     ...
;             { const int tn = (T + 3 < nt) ? T + 3 : nt - 1; M2_LOAD(u, tn); }
;             if (wvalid && T <= qblk) {
;                 const bf16_t* Kl = L0 + cur * M2STG;
;                 const bf16_t* Vl = Kl + M2K;
;                 const int key0 = T * 128;
;                 const int kbmax = (T < qblk) ? 3 : wi;
;                 f32x16 sc[4];
; #pragma unroll
;                 for (int kb = 0; kb < 4; ++kb) {
;                     if (kb <= kbmax) {
;                         sc[kb] = zero16();
; #pragma unroll
;                         for (int s6 = 0; s6 < 6; ++s6) sc[kb] = mfma32(ld16(Kl + (kb * 32 + l31) * KSTR + 16 * s6 + 8 * hh), qf[s6], sc[kb]);
;                     } else {
; #pragma unroll
;                         for (int r = 0; r < 16; ++r) sc[kb][r] = -1e30f;
;                     }
;                 }
;     ...
;             {
;                 bf16_t* S = L0 + (cur ^ 1) * M2STG;
;                 if (u == 0) M2_STORE(1, S) else if (u == 1) M2_STORE(2, S) else M2_STORE(0, S)
;             }
;             __syncthreads();
.LBB0_259:
	s_or_b64 exec, exec, s[66:67]
	s_xor_b32 s2, s59, 1
	s_mul_i32 s2, s2, 0xac00
	v_lshl_add_u32 v1, v209, 1, s2
	s_cmp_lt_u32 s62, s78
	v_lshl_add_u32 v234, v206, 1, s2
	v_lshl_add_u32 v235, v208, 1, s2
	v_add_u32_e32 v236, 0x6800, v1
	v_add_u32_e32 v237, 0x8800, v1
	s_cselect_b64 s[56:57], -1, 0
	s_cmp_ge_u32 s62, s78
	s_waitcnt vmcnt(9)
	ds_write_b128 v234, v[136:139]
	s_waitcnt vmcnt(8)
	ds_write_b128 v234, v[140:143] offset:13312
	s_waitcnt vmcnt(7)
	ds_write_b128 v235, v[148:151] offset:128
	s_waitcnt vmcnt(6)
	ds_write2_b64 v236, v[152:153], v[154:155] offset1:2
	s_waitcnt vmcnt(5)
	ds_write2_b64 v237, v[160:161], v[162:163] offset0:64 offset1:66
	s_waitcnt lgkmcnt(0)
	s_barrier
	s_cbranch_scc1 .LBB0_279
	s_add_i32 s2, s81, -1
	v_readlane_b32 s48, v253, 7
	v_readlane_b32 s49, v253, 8
	s_min_i32 s48, s2, s78
	s_lshl_b64 s[2:3], s[48:49], 17
	v_lshl_add_u64 v[2:3], v[200:201], 0, s[2:3]
	v_add_co_u32_e32 v4, vcc, 0x10000, v2
	s_lshl_b64 s[2:3], s[48:49], 13
	s_nop 0
	v_addc_co_u32_e32 v5, vcc, 0, v3, vcc
	global_load_dwordx4 v[136:139], v[2:3], off
	global_load_dwordx4 v[140:143], v[4:5], off
	v_lshl_add_u64 v[2:3], v[202:203], 0, s[2:3]
	s_mov_b32 s3, s49
	v_writelane_b32 v253, s2, 7
	global_load_dwordx4 v[148:151], v[2:3], off
	s_nop 0
	v_writelane_b32 v253, s3, 8
	s_lshl_b64 s[2:3], s[48:49], 8
	v_lshl_add_u64 v[2:3], v[204:205], 0, s[2:3]
	v_add_co_u32_e32 v4, vcc, 0x82000, v2
	s_add_i32 s3, s81, -4
	s_nop 0
	v_addc_co_u32_e32 v5, vcc, 0, v3, vcc
	global_load_dwordx4 v[152:155], v[2:3], off
	global_load_dwordx4 v[160:163], v[4:5], off
	v_cmp_lt_i32_e32 vcc, s62, v199
	s_and_b32 s2, s3, 1
	s_and_b64 s[48:49], s[64:65], vcc
	s_and_saveexec_b64 s[66:67], s[48:49]
	s_cbranch_execz .LBB0_278
	s_mul_i32 s48, s2, 0xac00
	v_or_b32_e32 v239, s48, v196
	v_add_u32_e32 v240, v239, v229
	ds_read_b128 v[2:5], v240
	ds_read_b128 v[6:9], v240 offset:32
	v_cmp_ge_i32_e32 vcc, s3, v199
	s_waitcnt lgkmcnt(1)
	v_mfma_f32_32x32x16_bf16 v[80:95], v[2:5], v[112:115], 0
	v_cndmask_b32_e32 v1, 3, v228, vcc
	s_waitcnt lgkmcnt(0)
	v_mfma_f32_32x32x16_bf16 v[80:95], v[6:9], v[116:119], v[80:95]
	ds_read_b128 v[2:5], v240 offset:64
	ds_read_b128 v[6:9], v240 offset:96
	s_waitcnt lgkmcnt(1)
	v_mfma_f32_32x32x16_bf16 v[80:95], v[2:5], v[120:123], v[80:95]
	ds_read_b128 v[2:5], v240 offset:128
	v_cmp_ne_u32_e64 s[52:53], 0, v1
	s_waitcnt lgkmcnt(1)
	v_mfma_f32_32x32x16_bf16 v[80:95], v[6:9], v[124:127], v[80:95]
	ds_read_b128 v[6:9], v240 offset:160
	s_waitcnt lgkmcnt(1)
	v_mfma_f32_32x32x16_bf16 v[80:95], v[2:5], v[128:131], v[80:95]
	s_waitcnt lgkmcnt(0)
	v_mfma_f32_32x32x16_bf16 v[80:95], v[6:9], v[132:135], v[80:95]
	s_and_saveexec_b64 s[48:49], s[52:53]
	s_cbranch_execz .Lmla_init_3
	ds_read_b128 v[2:5], v240 offset:6656
	ds_read_b128 v[212:215], v240 offset:6688
	ds_read_b128 v[216:219], v240 offset:6720
	ds_read_b128 v[220:223], v240 offset:6752
	s_waitcnt lgkmcnt(3)
	v_mfma_f32_32x32x16_bf16 v[96:111], v[2:5], v[112:115], 0
	ds_read_b128 v[2:5], v240 offset:6784
	s_waitcnt lgkmcnt(3)
	v_mfma_f32_32x32x16_bf16 v[96:111], v[212:215], v[116:119], v[96:111]
	ds_read_b128 v[212:215], v240 offset:6816
	s_waitcnt lgkmcnt(3)
	v_mfma_f32_32x32x16_bf16 v[96:111], v[216:219], v[120:123], v[96:111]
	s_waitcnt lgkmcnt(2)
	v_mfma_f32_32x32x16_bf16 v[96:111], v[220:223], v[124:127], v[96:111]
	s_waitcnt lgkmcnt(1)
	v_mfma_f32_32x32x16_bf16 v[96:111], v[2:5], v[128:131], v[96:111]
	s_waitcnt lgkmcnt(0)
	v_mfma_f32_32x32x16_bf16 v[96:111], v[212:215], v[132:135], v[96:111]

; DI void mla2_item(PP p, int item, unsigned char* lds) {
;     ...
;                     } else {
; #pragma unroll
;                         for (int r = 0; r < 16; ++r) sc[kb][r] = -1e30f;
;                     }
.LBB0_265:
	s_or_b64 exec, exec, s[48:49]
	v_cmp_eq_u32_e64 s[48:49], 3, v1
	s_and_saveexec_b64 s[62:63], s[48:49]
	s_cbranch_execz .Lmla_init_5
	ds_read_b128 v[2:5], v240 offset:19968
	ds_read_b128 v[212:215], v240 offset:20000
	ds_read_b128 v[216:219], v240 offset:20032
	ds_read_b128 v[220:223], v240 offset:20064
	s_waitcnt lgkmcnt(3)
	v_mfma_f32_32x32x16_bf16 v[64:79], v[2:5], v[112:115], 0
	ds_read_b128 v[2:5], v240 offset:20096
	s_waitcnt lgkmcnt(3)
	v_mfma_f32_32x32x16_bf16 v[64:79], v[212:215], v[116:119], v[64:79]
	ds_read_b128 v[212:215], v240 offset:20128
	s_waitcnt lgkmcnt(3)
	v_mfma_f32_32x32x16_bf16 v[64:79], v[216:219], v[120:123], v[64:79]
	s_waitcnt lgkmcnt(2)
	v_mfma_f32_32x32x16_bf16 v[64:79], v[220:223], v[124:127], v[64:79]
	s_waitcnt lgkmcnt(1)
	v_mfma_f32_32x32x16_bf16 v[64:79], v[2:5], v[128:131], v[64:79]
	s_waitcnt lgkmcnt(0)
	v_mfma_f32_32x32x16_bf16 v[64:79], v[212:215], v[132:135], v[64:79]

; DI f32x16 mfma32(bf16x8 a, bf16x8 b, f32x16 c) { return __builtin_amdgcn_mfma_f32_32x32x16_bf16(a, b, c, 0, 0, 0); }
; DI f32x16 zero16() { f32x16 z; for (int i = 0; i < 16; ++i) z[i] = 0.f; return z; }
; DI void mla2_item(PP p, int item, unsigned char* lds) {
;     ...
;             { const int tn = (T + 3 < nt) ? T + 3 : nt - 1; M2_LOAD(u, tn); }
;             if (wvalid && T <= qblk) {
;                 const bf16_t* Kl = L0 + cur * M2STG;
;                 const bf16_t* Vl = Kl + M2K;
;                 const int key0 = T * 128;
;                 const int kbmax = (T < qblk) ? 3 : wi;
;                 f32x16 sc[4];
; #pragma unroll
;                 for (int kb = 0; kb < 4; ++kb) {
;                     if (kb <= kbmax) {
;                         sc[kb] = zero16();
; #pragma unroll
;                         for (int s6 = 0; s6 < 6; ++s6) sc[kb] = mfma32(ld16(Kl + (kb * 32 + l31) * KSTR + 16 * s6 + 8 * hh), qf[s6], sc[kb]);
;                     } else {
; #pragma unroll
;                         for (int r = 0; r < 16; ++r) sc[kb][r] = -1e30f;
;                     }
;                 }
.LBB0_279:
	s_andn2_b64 vcc, exec, s[56:57]
	s_cbranch_vccnz .LBB0_240
	s_add_i32 s2, s81, -3
	s_cmp_gt_u32 s2, s78
	s_cbranch_scc1 .LBB0_240
	v_readlane_b32 s48, v253, 7
	v_readlane_b32 s49, v253, 8
	s_mov_b32 s51, s49
	s_min_i32 s50, s81, s78
	s_lshl_b64 s[48:49], s[50:51], 17
	v_lshl_add_u64 v[2:3], v[200:201], 0, s[48:49]
	v_add_co_u32_e32 v4, vcc, 0x10000, v2
	s_lshl_b64 s[48:49], s[50:51], 13
	s_nop 0
	v_addc_co_u32_e32 v5, vcc, 0, v3, vcc
	global_load_dwordx4 v[144:147], v[2:3], off
	global_load_dwordx4 v[156:159], v[4:5], off
	v_lshl_add_u64 v[2:3], v[202:203], 0, s[48:49]
	s_lshl_b64 s[48:49], s[50:51], 8
	global_load_dwordx4 v[164:167], v[2:3], off
	v_lshl_add_u64 v[2:3], v[204:205], 0, s[48:49]
	v_add_co_u32_e32 v4, vcc, 0x82000, v2
	s_mov_b32 s3, s51
	s_nop 0
	v_addc_co_u32_e32 v5, vcc, 0, v3, vcc
	global_load_dwordx4 v[168:171], v[2:3], off
	global_load_dwordx4 v[172:175], v[4:5], off
	v_writelane_b32 v253, s2, 7
	s_nop 1
	v_cmp_le_i32_e32 vcc, s2, v199
	v_writelane_b32 v253, s3, 8
	s_and_b64 s[48:49], s[64:65], vcc
	s_and_saveexec_b64 s[56:57], s[48:49]
	s_cbranch_execz .LBB0_239
	s_mul_i32 s59, s59, 0xac00
	v_or_b32_e32 v239, s59, v196
	v_add_u32_e32 v240, v239, v229
	ds_read_b128 v[2:5], v240
	ds_read_b128 v[6:9], v240 offset:32
	v_cmp_ge_i32_e32 vcc, s2, v199
	s_waitcnt lgkmcnt(1)
	v_mfma_f32_32x32x16_bf16 v[80:95], v[2:5], v[112:115], 0
	v_cndmask_b32_e32 v1, 3, v228, vcc
	s_waitcnt lgkmcnt(0)
	v_mfma_f32_32x32x16_bf16 v[80:95], v[6:9], v[116:119], v[80:95]
	ds_read_b128 v[2:5], v240 offset:64
	ds_read_b128 v[6:9], v240 offset:96
	s_waitcnt lgkmcnt(1)
	v_mfma_f32_32x32x16_bf16 v[80:95], v[2:5], v[120:123], v[80:95]
	ds_read_b128 v[2:5], v240 offset:128
	v_cmp_ne_u32_e64 s[52:53], 0, v1
	s_waitcnt lgkmcnt(1)
	v_mfma_f32_32x32x16_bf16 v[80:95], v[6:9], v[124:127], v[80:95]
	ds_read_b128 v[6:9], v240 offset:160
	s_waitcnt lgkmcnt(1)
	v_mfma_f32_32x32x16_bf16 v[80:95], v[2:5], v[128:131], v[80:95]
	s_waitcnt lgkmcnt(0)
	v_mfma_f32_32x32x16_bf16 v[80:95], v[6:9], v[132:135], v[80:95]
	s_and_saveexec_b64 s[48:49], s[52:53]
	s_cbranch_execz .Lmla_init_6
	ds_read_b128 v[2:5], v240 offset:6656
	ds_read_b128 v[212:215], v240 offset:6688
	ds_read_b128 v[216:219], v240 offset:6720
	ds_read_b128 v[220:223], v240 offset:6752
	s_waitcnt lgkmcnt(3)
	v_mfma_f32_32x32x16_bf16 v[96:111], v[2:5], v[112:115], 0
	ds_read_b128 v[2:5], v240 offset:6784
	s_waitcnt lgkmcnt(3)
	v_mfma_f32_32x32x16_bf16 v[96:111], v[212:215], v[116:119], v[96:111]
	ds_read_b128 v[212:215], v240 offset:6816
	s_waitcnt lgkmcnt(3)
	v_mfma_f32_32x32x16_bf16 v[96:111], v[216:219], v[120:123], v[96:111]
	s_waitcnt lgkmcnt(2)
	v_mfma_f32_32x32x16_bf16 v[96:111], v[220:223], v[124:127], v[96:111]
	s_waitcnt lgkmcnt(1)
	v_mfma_f32_32x32x16_bf16 v[96:111], v[2:5], v[128:131], v[96:111]
	s_waitcnt lgkmcnt(0)
	v_mfma_f32_32x32x16_bf16 v[96:111], v[212:215], v[132:135], v[96:111]

; DI void mla2_item(PP p, int item, unsigned char* lds) {
;     ...
;                     } else {
; #pragma unroll
;                         for (int r = 0; r < 16; ++r) sc[kb][r] = -1e30f;
;                     }
.Lmla_init_0:
	s_or_b64 exec, exec, s[48:49]
	v_mov_b32_e32 v96, v0
	v_mov_b32_e32 v97, v0
	v_mov_b32_e32 v98, v0
	v_mov_b32_e32 v99, v0
	v_mov_b32_e32 v100, v0
	v_mov_b32_e32 v101, v0
	v_mov_b32_e32 v102, v0
	v_mov_b32_e32 v103, v0
	v_mov_b32_e32 v104, v0
	v_mov_b32_e32 v105, v0
	v_mov_b32_e32 v106, v0
	v_mov_b32_e32 v107, v0
	v_mov_b32_e32 v108, v0
	v_mov_b32_e32 v109, v0
	v_mov_b32_e32 v110, v0
	v_mov_b32_e32 v111, v0
	s_branch .LBB0_244
.Lmla_init_1:
	s_or_b64 exec, exec, s[48:49]
	v_mov_b32_e32 v48, v0
	v_mov_b32_e32 v49, v0
	v_mov_b32_e32 v50, v0
	v_mov_b32_e32 v51, v0
	v_mov_b32_e32 v52, v0
	v_mov_b32_e32 v53, v0
	v_mov_b32_e32 v54, v0
	v_mov_b32_e32 v55, v0
	v_mov_b32_e32 v56, v0
	v_mov_b32_e32 v57, v0
	v_mov_b32_e32 v58, v0
	v_mov_b32_e32 v59, v0
	v_mov_b32_e32 v60, v0
	v_mov_b32_e32 v61, v0
	v_mov_b32_e32 v62, v0
	v_mov_b32_e32 v63, v0
	s_branch .LBB0_246
.Lmla_init_2:
	s_or_b64 exec, exec, s[56:57]
	v_mov_b32_e32 v64, v0
	v_mov_b32_e32 v65, v0
	v_mov_b32_e32 v66, v0
	v_mov_b32_e32 v67, v0
	v_mov_b32_e32 v68, v0
	v_mov_b32_e32 v69, v0
	v_mov_b32_e32 v70, v0
	v_mov_b32_e32 v71, v0
	v_mov_b32_e32 v72, v0
	v_mov_b32_e32 v73, v0
	v_mov_b32_e32 v74, v0
	v_mov_b32_e32 v75, v0
	v_mov_b32_e32 v76, v0
	v_mov_b32_e32 v77, v0
	v_mov_b32_e32 v78, v0
	v_mov_b32_e32 v79, v0
	s_branch .LBB0_248

; DI void mla2_item(PP p, int item, unsigned char* lds) {
;     ...
;                     } else {
; #pragma unroll
;                         for (int r = 0; r < 16; ++r) sc[kb][r] = -1e30f;
;                     }
.Lmla_init_5:
	s_or_b64 exec, exec, s[62:63]
	v_mov_b32_e32 v64, v0
	v_mov_b32_e32 v65, v0
	v_mov_b32_e32 v66, v0
	v_mov_b32_e32 v67, v0
	v_mov_b32_e32 v68, v0
	v_mov_b32_e32 v69, v0
	v_mov_b32_e32 v70, v0
	v_mov_b32_e32 v71, v0
	v_mov_b32_e32 v72, v0
	v_mov_b32_e32 v73, v0
	v_mov_b32_e32 v74, v0
	v_mov_b32_e32 v75, v0
	v_mov_b32_e32 v76, v0
	v_mov_b32_e32 v77, v0
	v_mov_b32_e32 v78, v0
	v_mov_b32_e32 v79, v0
	s_branch .LBB0_267

; DI int opaque_tid512() { int t = threadIdx.x; asm volatile("" : "+v"(t)); return t; }
; DI f32x16 zero16() { f32x16 z; for (int i = 0; i < 16; ++i) z[i] = 0.f; return z; }
; DI void ssd_b_item(PP p, int wg_item) {
;     const int tid = opaque_tid512(), lane = tid & 63, w8 = tid >> 6, hh = lane >> 5, l31 = lane & 31;
;     const int item = wg_item * 8 + w8;
;     const int seg = SSD_NSEG - 1 - item / 64, it64 = item % 64;
;     const int ph = it64 & 1, head = (it64 >> 1) & 15, b = it64 >> 5, g = head >> 3;
;     const int c_begin = (seg * NCH) / SSD_NSEG, c_end = ((seg + 1) * NCH) / SSD_NSEG;
;     f32x16 st[4]; st[0] = st[1] = st[2] = st[3] = zero16();
; #pragma unroll 2
;     for (int c = 0; c < c_begin; ++c) {
;         const int bc = b * NCH + c;
;         const bf16_t* lp = p->hb + ((((size_t)(bc * 16 + head) * 2 + ph) * 4) * 64 + lane) * 16;
;         u32x4 lc0[4], lc1[4];
; #pragma unroll
;         for (int nb = 0; nb < 4; ++nb) { lc0[nb] = *(const u32x4*)(lp + nb * 1024); lc1[nb] = *(const u32x4*)(lp + nb * 1024 + 8); }
.LBB0_302:
	s_andn2_b64 vcc, exec, s[0:1]
	s_cbranch_vccnz .LBB0_110
	v_mov_b32_e32 v78, v210
	s_mov_b32 s0, 0x15555556
	v_ashrrev_i32_e32 v1, 6, v78
	v_lshl_add_u32 v1, s80, 3, v1
	v_ashrrev_i32_e32 v2, 31, v1
	v_lshrrev_b32_e32 v2, 26, v2
	v_add_u32_e32 v2, v1, v2
	v_ashrrev_i32_e32 v3, 6, v2
	v_sub_u32_e32 v3, 0, v3
	v_and_b32_e32 v2, 0xffffffc0, v2
	v_lshl_add_u32 v80, v3, 6, v3
	v_sub_u32_e32 v2, v1, v2
	v_add_u32_e32 v3, 0x2cb, v80
	v_and_b32_e32 v79, 1, v2
	v_bfe_u32 v1, v2, 1, 4
	v_ashrrev_i32_e32 v2, 5, v2
	v_mul_hi_i32 v4, v3, s0
	v_and_b32_e32 v27, 63, v78
	v_lshrrev_b32_e32 v5, 31, v4
	v_mov_b32_e32 v87, 0
	v_mul_i32_i24_e32 v84, 0x2080, v2
	v_add_u32_e32 v82, v4, v5
	v_cmp_lt_i32_e32 vcc, 5, v3
	s_waitcnt vmcnt(2)
	v_mul_i32_i24_e32 v185, 0x41, v2
	v_lshlrev_b32_e32 v26, 5, v27
	v_ashrrev_i32_e32 v85, 31, v84
	v_mov_b32_e32 v86, v87
	v_mov_b32_e32 v89, v87
	v_mov_b32_e32 v88, v87
	v_mov_b32_e32 v91, v87
	v_mov_b32_e32 v90, v87
	v_mov_b32_e32 v93, v87
	v_mov_b32_e32 v92, v87
	v_mov_b32_e32 v95, v87
	v_mov_b32_e32 v94, v87
	v_mov_b32_e32 v97, v87
	v_mov_b32_e32 v96, v87
	v_mov_b32_e32 v99, v87
	v_mov_b32_e32 v98, v87
	v_mov_b32_e32 v101, v87
	v_mov_b32_e32 v100, v87
	v_mov_b32_e32 v103, v87
	v_mov_b32_e32 v102, v87
	v_mov_b32_e32 v105, v87
	v_mov_b32_e32 v104, v87
	v_mov_b32_e32 v107, v87
	v_mov_b32_e32 v106, v87
	v_mov_b32_e32 v109, v87
	v_mov_b32_e32 v108, v87
	v_mov_b32_e32 v111, v87
	v_mov_b32_e32 v110, v87
	v_mov_b32_e32 v113, v87
	v_mov_b32_e32 v112, v87
	v_mov_b32_e32 v115, v87
	v_mov_b32_e32 v114, v87
	v_mov_b32_e32 v117, v87
	v_mov_b32_e32 v116, v87
	v_mov_b32_e32 v119, v87
	v_mov_b32_e32 v118, v87
	v_mov_b32_e32 v121, v87
	v_mov_b32_e32 v120, v87
	v_mov_b32_e32 v123, v87
	v_mov_b32_e32 v122, v87
	v_mov_b32_e32 v125, v87
	v_mov_b32_e32 v124, v87
	v_mov_b32_e32 v127, v87
	v_mov_b32_e32 v126, v87
	v_mov_b32_e32 v131, v87
	v_mov_b32_e32 v130, v87
	v_mov_b32_e32 v133, v87
	v_mov_b32_e32 v132, v87
	v_mov_b32_e32 v135, v87
	v_mov_b32_e32 v134, v87
	v_mov_b32_e32 v129, v87
	v_mov_b32_e32 v128, v87
	v_mov_b32_e32 v137, v87
	v_mov_b32_e32 v136, v87
	v_mov_b32_e32 v139, v87
	v_mov_b32_e32 v138, v87
	v_mov_b32_e32 v141, v87
	v_mov_b32_e32 v140, v87
	v_mov_b32_e32 v143, v87
	v_mov_b32_e32 v142, v87
	v_mov_b32_e32 v145, v87
	v_mov_b32_e32 v144, v87
	v_mov_b32_e32 v147, v87
	v_mov_b32_e32 v146, v87
	v_mov_b32_e32 v149, v87
	v_mov_b32_e32 v148, v87
	s_and_saveexec_b64 s[0:1], vcc
	s_cbranch_execz .LBB0_311
	s_load_dwordx2 s[4:5], s[82:83], 0x130
	s_load_dwordx2 s[2:3], s[82:83], 0x150
	v_lshl_or_b32 v196, v79, 13, v26
	v_add_u32_e32 v6, 0x2c5, v80
	v_mov_b32_e32 v89, 0
	v_lshlrev_b64 v[4:5], 6, v[84:85]
	s_waitcnt lgkmcnt(0)
	v_lshl_add_u64 v[2:3], s[4:5], 0, v[196:197]
	v_cmp_lt_u32_e32 vcc, 5, v6
	v_mov_b32_e32 v28, 0
	v_mov_b32_e32 v88, v89
	v_mov_b32_e32 v91, v89
	v_mov_b32_e32 v90, v89
	v_mov_b32_e32 v93, v89
	v_mov_b32_e32 v92, v89
	v_mov_b32_e32 v95, v89
	v_mov_b32_e32 v94, v89
	v_mov_b32_e32 v97, v89
	v_mov_b32_e32 v96, v89
	v_mov_b32_e32 v99, v89
	v_mov_b32_e32 v98, v89
	v_mov_b32_e32 v101, v89
	v_mov_b32_e32 v100, v89
	v_mov_b32_e32 v87, v89
	v_mov_b32_e32 v86, v89
	v_mov_b32_e32 v105, v89
	v_mov_b32_e32 v104, v89
	v_mov_b32_e32 v107, v89
	v_mov_b32_e32 v106, v89
	v_mov_b32_e32 v109, v89
	v_mov_b32_e32 v108, v89
	v_mov_b32_e32 v111, v89
	v_mov_b32_e32 v110, v89
	v_mov_b32_e32 v113, v89
	v_mov_b32_e32 v112, v89
	v_mov_b32_e32 v115, v89
	v_mov_b32_e32 v114, v89
	v_mov_b32_e32 v117, v89
	v_mov_b32_e32 v116, v89
	v_mov_b32_e32 v103, v89
	v_mov_b32_e32 v102, v89
	v_mov_b32_e32 v121, v89
	v_mov_b32_e32 v120, v89
	v_mov_b32_e32 v123, v89
	v_mov_b32_e32 v122, v89
	v_mov_b32_e32 v125, v89
	v_mov_b32_e32 v124, v89
	v_mov_b32_e32 v127, v89
	v_mov_b32_e32 v126, v89
	v_mov_b32_e32 v131, v89
	v_mov_b32_e32 v130, v89
	v_mov_b32_e32 v133, v89
	v_mov_b32_e32 v132, v89
	v_mov_b32_e32 v135, v89
	v_mov_b32_e32 v134, v89
	v_mov_b32_e32 v119, v89
	v_mov_b32_e32 v118, v89
	v_mov_b32_e32 v137, v89
	v_mov_b32_e32 v136, v89
	v_mov_b32_e32 v139, v89
	v_mov_b32_e32 v138, v89
	v_mov_b32_e32 v141, v89
	v_mov_b32_e32 v140, v89
	v_mov_b32_e32 v143, v89
	v_mov_b32_e32 v142, v89
	v_mov_b32_e32 v145, v89
	v_mov_b32_e32 v144, v89
	v_mov_b32_e32 v147, v89
	v_mov_b32_e32 v146, v89
	v_mov_b32_e32 v149, v89
	v_mov_b32_e32 v148, v89
	v_mov_b32_e32 v129, v89
	v_mov_b32_e32 v128, v89
	s_and_saveexec_b64 s[4:5], vcc
	s_cbranch_execz .LBB0_308
	v_lshlrev_b32_e32 v196, 2, v1
	v_lshl_add_u64 v[8:9], v[4:5], 0, v[196:197]
	v_lshl_add_u64 v[8:9], s[2:3], 0, v[8:9]
	s_mov_b64 s[6:7], 0x3fc0
	v_mov_b32_e32 v128, 0
	v_and_b32_e32 v28, 0x1ffffffe, v82
	v_lshl_or_b32 v6, v185, 4, v1
	v_lshl_add_u64 v[8:9], v[8:9], 0, s[6:7]
	s_mov_b32 s8, 0
	s_mov_b64 s[6:7], 0
	v_mov_b32_e32 v129, v128
	v_mov_b32_e32 v148, v128
	v_mov_b32_e32 v149, v128
	v_mov_b32_e32 v146, v128
	v_mov_b32_e32 v147, v128
	v_mov_b32_e32 v144, v128
	v_mov_b32_e32 v145, v128
	v_mov_b32_e32 v142, v128
	v_mov_b32_e32 v143, v128
	v_mov_b32_e32 v140, v128
	v_mov_b32_e32 v141, v128
	v_mov_b32_e32 v138, v128
	v_mov_b32_e32 v139, v128
	v_mov_b32_e32 v136, v128
	v_mov_b32_e32 v137, v128
	v_mov_b32_e32 v118, v128
	v_mov_b32_e32 v119, v128
	v_mov_b32_e32 v134, v128
	v_mov_b32_e32 v135, v128
	v_mov_b32_e32 v132, v128
	v_mov_b32_e32 v133, v128
	v_mov_b32_e32 v130, v128
	v_mov_b32_e32 v131, v128
	v_mov_b32_e32 v126, v128
	v_mov_b32_e32 v127, v128
	v_mov_b32_e32 v124, v128
	v_mov_b32_e32 v125, v128
	v_mov_b32_e32 v122, v128
	v_mov_b32_e32 v123, v128
	v_mov_b32_e32 v120, v128
	v_mov_b32_e32 v121, v128
	v_mov_b32_e32 v102, v128
	v_mov_b32_e32 v103, v128
	v_mov_b32_e32 v116, v128
	v_mov_b32_e32 v117, v128
	v_mov_b32_e32 v114, v128
	v_mov_b32_e32 v115, v128
	v_mov_b32_e32 v112, v128
	v_mov_b32_e32 v113, v128
	v_mov_b32_e32 v110, v128
	v_mov_b32_e32 v111, v128
	v_mov_b32_e32 v108, v128
	v_mov_b32_e32 v109, v128
	v_mov_b32_e32 v106, v128
	v_mov_b32_e32 v107, v128
	v_mov_b32_e32 v104, v128
	v_mov_b32_e32 v105, v128
	v_mov_b32_e32 v86, v128
	v_mov_b32_e32 v87, v128
	v_mov_b32_e32 v100, v128
	v_mov_b32_e32 v101, v128
	v_mov_b32_e32 v98, v128
	v_mov_b32_e32 v99, v128
	v_mov_b32_e32 v96, v128
	v_mov_b32_e32 v97, v128
	v_mov_b32_e32 v94, v128
	v_mov_b32_e32 v95, v128
	v_mov_b32_e32 v92, v128
	v_mov_b32_e32 v93, v128
	v_mov_b32_e32 v90, v128
	v_mov_b32_e32 v91, v128
	v_mov_b32_e32 v88, v128
	v_mov_b32_e32 v89, v128
	s_mov_b64 s[10:11], 0x4000
	s_mov_b64 s[12:13], 0x1800

; DI f32x16 zero16() { f32x16 z; for (int i = 0; i < 16; ++i) z[i] = 0.f; return z; }
; DI void ssd_b_item(PP p, int wg_item) {
;     ...
;     for (int c = c_begin; c < c_end; ++c) {
;         const int bc = b * NCH + c;
;         const size_t r0 = (size_t)b * LSEQ + (size_t)c * 128;
;         const bf16_t* lp = p->hb + ((((size_t)(bc * 16 + head) * 2 + ph) * 4) * 64 + lane) * 16;
;         u32x4 lc0[4], lc1[4];
; #pragma unroll
;         for (int nb = 0; nb < 4; ++nb) { lc0[nb] = *(const u32x4*)(lp + nb * 1024); lc1[nb] = *(const u32x4*)(lp + nb * 1024 + 8); }
;         bf16x8 sp[4][2];
; #pragma unroll
;         for (int nb = 0; nb < 4; ++nb) { sp[nb][0] = pack_step(st[nb], 0); sp[nb][1] = pack_step(st[nb], 1); }
; #pragma unroll 2
;         for (int lb = 0; lb < 4; ++lb) {
;             const size_t lrow = r0 + lb * 32 + l31;
;             f32x16 yo = zero16();
;             const bf16_t* cp = p->cc + lrow * 256 + g * 128 + 4 * hh;
.LBB0_311:
	s_or_b64 exec, exec, s[0:1]
	v_add_u32_e32 v2, 0x30c, v80
	s_mov_b32 s0, 0x15555556
	v_mul_hi_i32 v2, v2, s0
	v_lshrrev_b32_e32 v3, 31, v2
	s_waitcnt vmcnt(1)
	v_add_u32_e32 v192, v2, v3
	v_cmp_lt_i32_e32 vcc, v82, v192
	s_and_saveexec_b64 s[0:1], vcc
	s_cbranch_execz .LBB0_109
	v_and_b32_e32 v5, 64, v211
	v_xor_b32_e32 v4, 32, v211
	v_add_u32_e32 v5, 64, v5
	s_load_dwordx2 s[2:3], s[82:83], 0x130
	s_load_dwordx2 s[4:5], s[82:83], 0xb0
	s_load_dwordx2 s[8:9], s[82:83], 0x150
	s_load_dwordx2 s[10:11], s[82:83], 0xd8
	v_cmp_lt_i32_e32 vcc, v4, v5
	v_lshlrev_b32_e32 v196, 13, v79
	v_cmp_gt_u32_e64 s[6:7], 32, v27
	v_cndmask_b32_e32 v4, v211, v4, vcc
	v_lshlrev_b32_e32 v193, 2, v4
	v_mov_b32_e32 v27, v197
	s_waitcnt lgkmcnt(0)
	v_lshl_add_u64 v[4:5], s[2:3], 0, v[196:197]
	v_ashrrev_i32_e32 v83, 31, v82
	v_lshl_add_u64 v[152:153], v[4:5], 0, v[26:27]
	v_lshlrev_b64 v[4:5], 14, v[82:83]
	v_lshlrev_b64 v[6:7], 7, v[84:85]
	v_lshl_add_u64 v[154:155], v[4:5], 0, v[6:7]
	v_and_b32_e32 v10, 31, v78
	v_lshrrev_b32_e32 v2, 3, v78
	v_lshl_or_b32 v4, v10, 7, v154
	v_lshlrev_b32_e32 v5, 3, v1
	v_lshlrev_b32_e32 v6, 2, v79
	v_and_b32_e32 v8, 4, v2
	v_lshlrev_b32_e32 v2, 2, v1
	v_mov_b32_e32 v3, v197
	v_or3_b32 v154, v4, v5, v6
	v_mad_i64_i32 v[4:5], s[2:3], v84, s20, 0
	v_lshl_add_u64 v[150:151], s[8:9], 0, v[2:3]
	v_lshlrev_b32_e32 v3, 6, v1
	v_lshlrev_b32_e32 v9, 5, v79
	s_mov_b32 s2, 0x10a000
	v_mad_i64_i32 v[4:5], s[2:3], v82, s2, v[4:5]
	v_or3_b32 v3, v3, v9, v8
	v_mad_u64_u32 v[4:5], s[2:3], v10, s20, v[4:5]
	v_lshlrev_b32_e32 v196, 1, v3
	v_lshl_add_u64 v[6:7], v[4:5], 0, v[196:197]
	v_lshl_add_u64 v[156:157], s[4:5], 0, v[6:7]
	v_or_b32_e32 v6, 48, v196
	v_mov_b32_e32 v7, v197
	v_lshl_add_u64 v[6:7], v[4:5], 0, v[6:7]
	v_lshl_add_u64 v[158:159], s[4:5], 0, v[6:7]
	v_or_b32_e32 v6, 32, v196
	v_mov_b32_e32 v7, v197
	v_or_b32_e32 v196, 16, v196
	v_lshl_add_u64 v[6:7], v[4:5], 0, v[6:7]
	v_lshl_add_u64 v[4:5], v[4:5], 0, v[196:197]
	s_waitcnt vmcnt(0)
	v_lshl_add_u64 v[160:161], s[4:5], 0, v[6:7]
	v_lshl_add_u64 v[162:163], s[4:5], 0, v[4:5]
	v_lshrrev_b32_e32 v3, 2, v78
	v_lshlrev_b64 v[4:5], 7, v[82:83]
	v_or_b32_e32 v6, v84, v10
	v_mov_b32_e32 v7, v85
	v_and_b32_e32 v196, 8, v3
	v_lshl_add_u64 v[4:5], v[6:7], 0, v[4:5]
	v_lshlrev_b32_e32 v3, 5, v1
	v_lshlrev_b64 v[8:9], 9, v[4:5]
	v_and_b32_e32 v3, 0x100, v3
	v_or_b32_e32 v8, v8, v3
	v_lshl_add_u64 v[164:165], s[10:11], 0, v[8:9]
	v_lshlrev_b64 v[8:9], 16, v[82:83]
	v_lshlrev_b64 v[6:7], 9, v[6:7]
	v_lshl_add_u64 v[6:7], v[8:9], 0, v[6:7]
	v_or_b32_e32 v6, v6, v3
	v_lshlrev_b64 v[4:5], 6, v[4:5]
	v_lshl_add_u64 v[6:7], s[10:11], 0, v[6:7]
	s_mov_b64 s[2:3], 0x4080
	v_or_b32_e32 v4, v4, v2
	v_lshl_add_u64 v[166:167], v[6:7], 0, s[2:3]
	v_lshl_add_u64 v[168:169], s[8:9], 0, v[4:5]
	s_mov_b64 s[2:3], 0
	s_branch .LBB0_314
